# norm / norm-mix phases: waves enumerated as wave*256 + block so the short third loop trip runs on wave 0 of every workgroup instead of all waves of 32 workgroups
# speedup vs baseline: 1.0049x; 1.0049x over previous
; __device__ __forceinline__ void phase_norm_mix(const Fr& F, int l, int jr, int nmix, int n0, int n1, int n2, int n3) {
;     const int nidx[4] = {n0, n1, n2, n3};
;     for (int run = F.gw; run < NT / 4; run += GRID * NWAVES) {
;         const int m0 = run * 4, b = m0 / TB, t0 = m0 - b * TB, seg_lo = b * TB + (t0 < CTXL ? 0 : CTXL), seg_hi = b * TB + (t0 < CTXL ? CTXL : TB);
;         f32x4 h[6][4];
;         load_rows<6>(F, l, m0 - 1, seg_lo, seg_hi, h); norm_rows<6>(F, l, m0, h);
.LBB0_48:
	s_cmpk_lt_i32 s36, 0x1100
	v_cmp_gt_i32_e32 vcc, 2, v1
	s_cselect_b64 s[38:39], -1, 0
	v_cmp_lt_i32_e64 s[6:7], 1, v2
	s_and_b64 s[8:9], vcc, s[38:39]
	s_and_b64 s[6:7], s[8:9], s[6:7]
	v_lshlrev_b32_e32 v132, 4, v130
	v_lshlrev_b32_e32 v134, 3, v130
	s_and_saveexec_b64 s[8:9], s[6:7]
	s_cbranch_execz .LBB0_106
	s_load_dwordx2 s[6:7], s[0:1], 0x20
	s_load_dwordx2 s[10:11], s[0:1], 0x38
	v_mov_b32_e32 v113, 0
	v_mov_b32_e32 v133, v113
	v_mov_b32_e32 v135, v113
	s_waitcnt lgkmcnt(0)
	v_lshl_add_u64 v[114:115], s[6:7], 0, v[132:133]
	v_lshl_add_u64 v[0:1], s[26:27], 0, v[134:135]
	s_mov_b64 s[6:7], 0x1200000
	v_lshl_add_u64 v[118:119], v[0:1], 0, s[6:7]
	s_mov_b64 s[6:7], 0x3400000
	v_lshl_add_u64 v[116:117], s[10:11], 0, v[132:133]
	v_lshl_add_u64 v[122:123], v[0:1], 0, s[6:7]
	s_mov_b64 s[6:7], 0x4000
	v_lshl_add_u64 v[124:125], v[116:117], 0, s[6:7]
	s_mov_b64 s[6:7], 0x5600000
	v_lshl_add_u64 v[126:127], v[0:1], 0, s[6:7]
	s_mov_b64 s[6:7], 0x5000
	s_add_u32 s10, s0, 16
	v_lshl_add_u64 v[136:137], v[116:117], 0, s[6:7]
	s_mov_b64 s[6:7], 0x7800000
	s_addc_u32 s11, s1, 0
	s_mov_b64 s[12:13], 0x1000
	v_lshl_add_u64 v[138:139], v[0:1], 0, s[6:7]
	s_lshl_b32 s3, s2, 2
	s_lshl_b32 s6, s68, 10
	v_lshl_add_u64 v[120:121], v[116:117], 0, s[12:13]
	s_add_i32 s14, s3, s6
	s_movk_i32 s3, 0x100
	v_lshlrev_b32_e32 v112, 4, v130
	s_movk_i32 s37, 0x1000
	v_mov_b32_e32 v129, 0x358637bd
	s_mov_b32 s48, 0xf800000
	v_mov_b32_e32 v131, 0x260
	s_lshl_b32 s49, s68, 8
	s_add_i32 s49, s49, s2
	s_branch .LBB0_52

; __device__ __forceinline__ void phase_norm_mix(const Fr& F, int l, int jr, int nmix, int n0, int n1, int n2, int n3) {
;     const int nidx[4] = {n0, n1, n2, n3};
;     for (int run = F.gw; run < NT / 4; run += GRID * NWAVES) {
;         const int m0 = run * 4, b = m0 / TB, t0 = m0 - b * TB, seg_lo = b * TB + (t0 < CTXL ? 0 : CTXL), seg_hi = b * TB + (t0 < CTXL ? CTXL : TB);
;         f32x4 h[6][4];
;         load_rows<6>(F, l, m0 - 1, seg_lo, seg_hi, h); norm_rows<6>(F, l, m0, h);
.LBB0_303:
	s_or_b64 exec, exec, s[6:7]
	v_cmp_gt_i32_e32 vcc, 4, v1
	v_cmp_lt_i32_e64 s[6:7], 3, v2
	s_and_b64 s[6:7], vcc, s[6:7]
	s_and_b64 s[6:7], s[6:7], s[38:39]
	s_and_saveexec_b64 s[8:9], s[6:7]
	s_cbranch_execz .LBB0_361
	s_load_dwordx2 s[6:7], s[0:1], 0x20
	s_load_dwordx2 s[10:11], s[0:1], 0x38
	v_mov_b32_e32 v113, 0
	v_mov_b32_e32 v133, v113
	v_mov_b32_e32 v135, v113
	s_waitcnt lgkmcnt(0)
	v_lshl_add_u64 v[114:115], s[6:7], 0, v[132:133]
	v_lshl_add_u64 v[0:1], s[10:11], 0, v[132:133]
	s_mov_b64 s[6:7], 0x2000
	v_lshl_add_u64 v[116:117], v[0:1], 0, s[6:7]
	v_lshl_add_u64 v[2:3], s[26:27], 0, v[134:135]
	s_mov_b64 s[6:7], 0x1200000
	v_lshl_add_u64 v[118:119], v[2:3], 0, s[6:7]
	s_mov_b64 s[6:7], 0x3000
	s_add_u32 s10, s0, 16
	v_lshl_add_u64 v[120:121], v[0:1], 0, s[6:7]
	s_mov_b64 s[6:7], 0x3400000
	s_addc_u32 s11, s1, 0
	v_lshl_add_u64 v[122:123], v[2:3], 0, s[6:7]
	s_lshl_b32 s3, s2, 2
	s_lshl_b32 s6, s68, 10
	s_add_i32 s12, s3, s6
	s_movk_i32 s3, 0x100
	v_lshlrev_b32_e32 v112, 4, v130
	s_mov_b64 s[14:15], 0x1000
	s_movk_i32 s37, 0x1000
	v_mov_b32_e32 v129, 0x358637bd
	s_mov_b32 s48, 0xf800000
	v_mov_b32_e32 v131, 0x260
	s_lshl_b32 s49, s68, 8
	s_add_i32 s49, s49, s2
	s_branch .LBB0_307

;     __device__ __forceinline__ bf16* R(int i) const { return (bf16*)(ws + OFF_R0 + (size_t)i * RSZ); }
; __device__ __forceinline__ void phase_norm_plain(const Fr& F, int l) {
;     for (int run = F.gw; run < NT / 4; run += GRID * NWAVES) {
;         const int m0 = run * 4; f32x4 h[4][4];
;         load_rows<4>(F, l, m0, 0, NT, h); norm_rows<4>(F, l, m0, h);
; #pragma unroll
;         for (int r = 0; r < 4; ++r) store_row_bf16(F.R(0) + (size_t)(m0 + r) * D, F.lane, h[r]);
.LBB0_828:
	s_cmp_lt_i32 s34, 9
	s_cselect_b64 s[6:7], -1, 0
	s_cmp_gt_i32 s35, 8
	s_cselect_b64 s[8:9], -1, 0
	s_and_b64 s[6:7], s[6:7], s[8:9]
	s_and_b64 s[6:7], s[6:7], s[38:39]
	s_andn2_b64 vcc, exec, s[6:7]
	s_cbranch_vccnz .LBB0_863
	s_load_dwordx2 s[6:7], s[0:1], 0x20
	s_load_dwordx2 s[8:9], s[0:1], 0x130
	v_mov_b32_e32 v81, 0
	s_add_u32 s3, s26, 0xf000
	v_mov_b32_e32 v133, v81
	s_addc_u32 s24, s27, 0
	s_waitcnt lgkmcnt(0)
	v_lshl_add_u64 v[0:1], s[6:7], 0, v[132:133]
	s_mov_b64 s[10:11], 0x1000
	v_mov_b32_e32 v135, v81
	v_lshl_add_u64 v[82:83], v[0:1], 0, s[10:11]
	v_lshl_add_u64 v[0:1], s[26:27], 0, v[134:135]
	s_mov_b64 s[6:7], 0x1200000
	s_add_u32 s12, s26, 0x300000
	v_lshl_add_u64 v[84:85], v[0:1], 0, s[6:7]
	s_addc_u32 s13, s27, 0
	s_lshl_b32 s6, s2, 2
	s_lshl_b32 s7, s68, 10
	s_add_i32 s6, s6, s7
	s_or_b32 s14, s6, 3
	v_lshlrev_b32_e32 v80, 4, v130
	s_movk_i32 s25, 0x1000
	v_mov_b32_e32 v102, 0x358637bd
	s_mov_b32 s42, 0xf800000
	v_mov_b32_e32 v103, 0x260
	s_lshl_b32 s43, s68, 8
	s_add_i32 s43, s43, s2
	s_branch .LBB0_831

;     __device__ __forceinline__ bf16* R(int i) const { return (bf16*)(ws + OFF_R0 + (size_t)i * RSZ); }
; __device__ __forceinline__ void phase_norm_plain(const Fr& F, int l) {
;     for (int run = F.gw; run < NT / 4; run += GRID * NWAVES) {
;         const int m0 = run * 4; f32x4 h[4][4];
;         load_rows<4>(F, l, m0, 0, NT, h); norm_rows<4>(F, l, m0, h);
; #pragma unroll
;         for (int r = 0; r < 4; ++r) store_row_bf16(F.R(0) + (size_t)(m0 + r) * D, F.lane, h[r]);
.LBB0_1332:
	s_cmp_lt_i32 s34, 14
	s_cselect_b64 s[6:7], -1, 0
	s_cmp_gt_i32 s35, 13
	s_cselect_b64 s[8:9], -1, 0
	s_and_b64 s[6:7], s[6:7], s[8:9]
	s_and_b64 s[6:7], s[6:7], s[38:39]
	s_andn2_b64 vcc, exec, s[6:7]
	s_cbranch_vccnz .LBB0_1367
	s_load_dwordx2 s[6:7], s[0:1], 0x20
	s_load_dwordx2 s[8:9], s[0:1], 0x130
	v_mov_b32_e32 v81, 0
	s_add_u32 s3, s26, 0x1e000
	v_mov_b32_e32 v133, v81
	s_addc_u32 s24, s27, 0
	s_waitcnt lgkmcnt(0)
	v_lshl_add_u64 v[0:1], s[6:7], 0, v[132:133]
	s_mov_b64 s[6:7], 0x2000
	v_mov_b32_e32 v135, v81
	v_lshl_add_u64 v[82:83], v[0:1], 0, s[6:7]
	v_lshl_add_u64 v[0:1], s[26:27], 0, v[134:135]
	s_mov_b64 s[6:7], 0x1200000
	s_add_u32 s10, s26, 0x300000
	v_lshl_add_u64 v[84:85], v[0:1], 0, s[6:7]
	s_addc_u32 s11, s27, 0
	s_lshl_b32 s6, s2, 2
	s_lshl_b32 s7, s68, 10
	s_add_i32 s6, s6, s7
	s_or_b32 s12, s6, 3
	v_lshlrev_b32_e32 v80, 4, v130
	s_mov_b64 s[14:15], 0x1000
	s_movk_i32 s25, 0x1000
	v_mov_b32_e32 v102, 0x358637bd
	s_mov_b32 s42, 0xf800000
	v_mov_b32_e32 v103, 0x260
	s_lshl_b32 s43, s68, 8
	s_add_i32 s43, s43, s2
	s_branch .LBB0_1335

; __device__ __forceinline__ void phase_norm_mix(const Fr& F, int l, int jr, int nmix, int n0, int n1, int n2, int n3) {
;     const int nidx[4] = {n0, n1, n2, n3};
;     for (int run = F.gw; run < NT / 4; run += GRID * NWAVES) {
;         const int m0 = run * 4, b = m0 / TB, t0 = m0 - b * TB, seg_lo = b * TB + (t0 < CTXL ? 0 : CTXL), seg_hi = b * TB + (t0 < CTXL ? CTXL : TB);
;         f32x4 h[6][4];
;         load_rows<6>(F, l, m0 - 1, seg_lo, seg_hi, h); norm_rows<6>(F, l, m0, h);
.LBB0_2028:
	s_cmp_lt_i32 s34, 22
	s_cselect_b64 s[6:7], -1, 0
	s_cmp_gt_i32 s35, 21
	s_cselect_b64 s[8:9], -1, 0
	s_and_b64 s[6:7], s[6:7], s[8:9]
	s_and_b64 s[6:7], s[6:7], s[38:39]
	s_andn2_b64 vcc, exec, s[6:7]
	s_cbranch_vccnz .LBB0_2085
	s_load_dwordx2 s[6:7], s[0:1], 0x20
	s_load_dwordx2 s[10:11], s[0:1], 0x38
	s_load_dwordx2 s[8:9], s[0:1], 0x130
	v_mov_b32_e32 v113, 0
	v_mov_b32_e32 v133, v113
	v_mov_b32_e32 v135, v113
	s_waitcnt lgkmcnt(0)
	v_lshl_add_u64 v[0:1], s[6:7], 0, v[132:133]
	s_mov_b64 s[6:7], 0x3000
	v_lshl_add_u64 v[114:115], v[0:1], 0, s[6:7]
	v_lshl_add_u64 v[0:1], s[10:11], 0, v[132:133]
	s_mov_b64 s[6:7], 0x6000
	v_lshl_add_u64 v[116:117], v[0:1], 0, s[6:7]
	v_lshl_add_u64 v[2:3], s[26:27], 0, v[134:135]
	s_mov_b64 s[6:7], 0x1200000
	v_lshl_add_u64 v[118:119], v[2:3], 0, s[6:7]
	s_mov_b64 s[6:7], 0x7000
	v_lshl_add_u64 v[120:121], v[0:1], 0, s[6:7]
	s_mov_b64 s[6:7], 0x3400000
	v_lshl_add_u64 v[122:123], v[2:3], 0, s[6:7]
	s_mov_b64 s[6:7], 0xa000
	s_add_u32 s3, s26, 0x2d000
	v_lshl_add_u64 v[124:125], v[0:1], 0, s[6:7]
	s_mov_b64 s[6:7], 0x5600000
	s_addc_u32 s37, s27, 0
	v_lshl_add_u64 v[126:127], v[2:3], 0, s[6:7]
	s_mov_b64 s[6:7], 0xb000
	s_add_u32 s10, s26, 0x300000
	v_lshl_add_u64 v[136:137], v[0:1], 0, s[6:7]
	s_mov_b64 s[6:7], 0x7800000
	s_addc_u32 s11, s27, 0
	v_lshl_add_u64 v[138:139], v[2:3], 0, s[6:7]
	s_lshl_b32 s6, s2, 2
	s_lshl_b32 s7, s68, 10
	s_add_i32 s12, s6, s7
	s_movk_i32 s50, 0x100
	v_lshlrev_b32_e32 v112, 4, v130
	s_mov_b64 s[14:15], 0x1000
	s_movk_i32 s51, 0x1000
	v_mov_b32_e32 v129, 0x358637bd
	s_mov_b32 s52, 0xf800000
	v_mov_b32_e32 v133, 0x260
	s_lshl_b32 s53, s68, 8
	s_add_i32 s53, s53, s2
	s_branch .LBB0_2032

; __device__ __forceinline__ void phase_norm_mix(const Fr& F, int l, int jr, int nmix, int n0, int n1, int n2, int n3) {
;     const int nidx[4] = {n0, n1, n2, n3};
;     for (int run = F.gw; run < NT / 4; run += GRID * NWAVES) {
;         const int m0 = run * 4, b = m0 / TB, t0 = m0 - b * TB, seg_lo = b * TB + (t0 < CTXL ? 0 : CTXL), seg_hi = b * TB + (t0 < CTXL ? CTXL : TB);
;         f32x4 h[6][4];
;         load_rows<6>(F, l, m0 - 1, seg_lo, seg_hi, h); norm_rows<6>(F, l, m0, h);
.LBB0_2282:
	s_cmp_lt_i32 s34, 24
	s_cselect_b64 s[6:7], -1, 0
	s_cmp_gt_i32 s35, 23
	s_cselect_b64 s[8:9], -1, 0
	s_and_b64 s[6:7], s[6:7], s[8:9]
	s_and_b64 s[6:7], s[6:7], s[38:39]
	s_andn2_b64 vcc, exec, s[6:7]
	s_cbranch_vccnz .LBB0_2339
	s_load_dwordx2 s[6:7], s[0:1], 0x20
	s_load_dwordx2 s[10:11], s[0:1], 0x38
	s_load_dwordx2 s[8:9], s[0:1], 0x130
	v_mov_b32_e32 v135, 0
	v_mov_b32_e32 v133, v135
	s_add_u32 s3, s26, 0x2d000
	s_waitcnt lgkmcnt(0)
	v_lshl_add_u64 v[0:1], s[6:7], 0, v[132:133]
	s_mov_b64 s[6:7], 0x3000
	v_lshl_add_u64 v[112:113], v[0:1], 0, s[6:7]
	v_lshl_add_u64 v[0:1], s[10:11], 0, v[132:133]
	s_mov_b64 s[6:7], 0x8000
	v_lshl_add_u64 v[114:115], v[0:1], 0, s[6:7]
	v_lshl_add_u64 v[2:3], s[26:27], 0, v[134:135]
	s_mov_b64 s[6:7], 0x1200000
	s_addc_u32 s37, s27, 0
	v_lshl_add_u64 v[116:117], v[2:3], 0, s[6:7]
	s_mov_b64 s[6:7], 0x9000
	s_add_u32 s10, s26, 0x300000
	v_lshl_add_u64 v[118:119], v[0:1], 0, s[6:7]
	s_mov_b64 s[6:7], 0x3400000
	s_addc_u32 s11, s27, 0
	v_lshl_add_u64 v[120:121], v[2:3], 0, s[6:7]
	s_lshl_b32 s6, s2, 2
	s_lshl_b32 s7, s68, 10
	s_add_i32 s12, s6, s7
	s_movk_i32 s48, 0x100
	v_lshlrev_b32_e32 v134, 4, v130
	s_mov_b64 s[14:15], 0x1000
	s_movk_i32 s49, 0x1000
	v_mov_b32_e32 v129, 0x358637bd
	s_mov_b32 s50, 0xf800000
	v_mov_b32_e32 v133, 0x260
	s_lshl_b32 s51, s68, 8
	s_add_i32 s51, s51, s2
	s_branch .LBB0_2286
